# v21 + counted vmcnt at the first k-tile of later ffn_in tiles (epilogue stores stay in flight)
# speedup vs baseline: 1.0114x; 1.0001x over previous
;     ...
;     for (int kt = 0; kt < nk; ++kt) {
;         asm volatile("s_waitcnt vmcnt(0)\n\ts_barrier" ::: "memory");
;         if (kt + 1 < nk) issue(kt + 1, (kt + 1) & 1);
.LBB0_789:
	s_cmp_lg_u32 s31, 0
	s_cbranch_scc1 .Lffn_fullw
	s_cmp_eq_u32 s17, 0
	s_cbranch_scc1 .Lffn_fullw
	s_waitcnt vmcnt(8)
	s_branch .Lffn_bar2

;     ...
;     auto issue = [&](int kt, int st) {
;         glds_tile8(va, vb, a0p + (size_t)kt * kstepA, Btile + (size_t)kt * 64, __builtin_amdgcn_readfirstlane(lds0 + st * 32768));
;     };
;     ...
;     for (int kt = 0; kt < nk; ++kt) {
;         asm volatile("s_waitcnt vmcnt(0)\n\ts_barrier" ::: "memory");
;         if (kt + 1 < nk) issue(kt + 1, (kt + 1) & 1);
.Lffn_bar2:
	s_barrier
	s_cmp_lg_u32 s31, 0x78000
	s_mov_b64 s[24:25], -1
	s_cbranch_scc0 .LBB0_791
	s_add_i32 s34, s31, 0x8000
	s_and_b32 s24, s34, 0x8000
	s_add_i32 s24, s27, s24
	s_mov_b32 s25, m0
	s_mov_b32 m0, s24
	s_nop 0
	global_load_lds_dwordx4 v0, s[14:15]
	s_add_u32 m0, m0, 0x1000
	s_nop 0
	global_load_lds_dwordx4 v68, s[14:15]
	s_add_u32 m0, m0, 0x1000
	s_nop 0
	global_load_lds_dwordx4 v69, s[14:15]
	s_add_u32 m0, m0, 0x1000
	s_nop 0
	global_load_lds_dwordx4 v71, s[14:15]
	s_add_u32 m0, m0, 0x1000
	s_nop 0
	global_load_lds_dwordx4 v0, s[10:11]
	s_add_u32 m0, m0, 0x1000
	s_nop 0
	global_load_lds_dwordx4 v68, s[10:11]
	s_add_u32 m0, m0, 0x1000
	s_nop 0
	global_load_lds_dwordx4 v69, s[10:11]
	s_add_u32 m0, m0, 0x1000
	s_nop 0
	global_load_lds_dwordx4 v71, s[10:11]
	s_mov_b32 m0, s25
	s_mov_b64 s[24:25], 0
